# mini_ring loop top: address VALU and w<4 flag hoisted above the chunk barrier; LDS-DMA m0 save/restore dropped in the loop
# baseline (speedup 1.0000x reference)
; #define MR_ISSUE(c) do { const unsigned sb_ = ldw + (unsigned)(((c) & (NS - 1)) * SLOT); glds16_m(src[0] + (size_t)(c) * 128, sb_); glds16_m(src[1] + (size_t)(c) * 128, sb_ + 8192u); } while (0)
; template <class Epi>
; __device__ __forceinline__ void mini_ring(PG8_LAS unsigned char* lds, const bf16_t* A, const bf16_t* Bt, int K, const Epi& E, int mu, int wave_u) {
;     ...
; #pragma unroll
;     for (int c = 0; c < PD; ++c) MR_ISSUE(c);
;     f32x4 acc[2][2];
; #pragma unroll
;     for (int b = 0; b < 2; ++b)
; #pragma unroll
;         for (int n = 0; n < 2; ++n) acc[b][n] = (f32x4){0.f, 0.f, 0.f, 0.f};
;     const int x0 = ((fq) ^ (fr & 7)) * 16, x1 = ((4 + fq) ^ (fr & 7)) * 16;
;     const int aoff = (16 * (w & 3) + fr) * 128;
;     ...
; #pragma unroll 1
;     for (int c = 0; c < nmain; ++c) {
;         MR_ISSUE(c + PD);
;         asm volatile("s_waitcnt vmcnt(12)" ::: "memory"); __builtin_amdgcn_s_barrier(); asm volatile("" ::: "memory");
;         MR_CONSUME(c);
;     }
.LBB0_201:
	s_add_i32 s10, s1, 0x18000
	s_and_b32 s10, s10, 0x1c000
	s_add_i32 s10, s10, s0
	s_mov_b32 m0, s10
	s_nop 0
	global_load_lds_dwordx4 v[22:23], off
	s_addk_i32 s10, 0x2000
	s_mov_b32 m0, s10
	s_nop 0
	global_load_lds_dwordx4 v[20:21], off
	v_cndmask_b32_e64 v0, 0, 1, s[16:17]
	v_cmp_ne_u32_e64 s[10:11], 1, v0
	s_and_b32 s24, s1, 0x1c000
	v_add_u32_e32 v0, s24, v28
	v_add_u32_e32 v29, v0, v26
	v_add_u32_e32 v2, s24, v27
	v_add_u32_e32 v3, v2, v26
	v_add_u32_e32 v0, v0, v25
	v_add_u32_e32 v2, v2, v25
	s_andn2_b64 vcc, exec, s[16:17]
	s_waitcnt vmcnt(12)
	s_barrier
	s_cbranch_vccnz .LBB0_200
	ds_read_b128 v[34:37], v3
	ds_read_b128 v[30:33], v29 offset:8192
	ds_read_b128 v[44:47], v29 offset:10240
	ds_read_b128 v[48:51], v29 offset:12288
	ds_read_b128 v[56:59], v29 offset:14336
	ds_read_b128 v[38:41], v2
	ds_read_b128 v[64:67], v0 offset:8192
	ds_read_b128 v[68:71], v0 offset:10240
	s_waitcnt lgkmcnt(6)
	v_mfma_f32_16x16x32_bf16 v[16:19], v[30:33], v[34:37], v[16:19]
	ds_read_b128 v[30:33], v0 offset:12288
	s_waitcnt lgkmcnt(6)
	v_mfma_f32_16x16x32_bf16 v[12:15], v[44:47], v[34:37], v[12:15]
	ds_read_b128 v[44:47], v0 offset:14336
	s_waitcnt lgkmcnt(6)
	v_mfma_f32_16x16x32_bf16 v[4:7], v[48:51], v[34:37], v[4:7]
	s_waitcnt lgkmcnt(5)
	v_mfma_f32_16x16x32_bf16 v[8:11], v[56:59], v[34:37], v[8:11]
	s_waitcnt lgkmcnt(3)
	v_mfma_f32_16x16x32_bf16 v[16:19], v[64:67], v[38:41], v[16:19]
	s_waitcnt lgkmcnt(2)
	v_mfma_f32_16x16x32_bf16 v[12:15], v[68:71], v[38:41], v[12:15]
	s_waitcnt lgkmcnt(1)
	v_mfma_f32_16x16x32_bf16 v[4:7], v[30:33], v[38:41], v[4:7]
	s_waitcnt lgkmcnt(0)
	v_mfma_f32_16x16x32_bf16 v[8:11], v[44:47], v[38:41], v[8:11]
	s_branch .LBB0_200

; #define MR_ISSUE(c) do { const unsigned sb_ = ldw + (unsigned)(((c) & (NS - 1)) * SLOT); glds16_m(src[0] + (size_t)(c) * 128, sb_); glds16_m(src[1] + (size_t)(c) * 128, sb_ + 8192u); } while (0)
; template <class Epi>
; __device__ __forceinline__ void mini_ring(PG8_LAS unsigned char* lds, const bf16_t* A, const bf16_t* Bt, int K, const Epi& E, int mu, int wave_u) {
;     ...
; #pragma unroll
;     for (int c = 0; c < PD; ++c) MR_ISSUE(c);
;     f32x4 acc[2][2];
; #pragma unroll
;     for (int b = 0; b < 2; ++b)
; #pragma unroll
;         for (int n = 0; n < 2; ++n) acc[b][n] = (f32x4){0.f, 0.f, 0.f, 0.f};
;     const int x0 = ((fq) ^ (fr & 7)) * 16, x1 = ((4 + fq) ^ (fr & 7)) * 16;
;     const int aoff = (16 * (w & 3) + fr) * 128;
;     ...
; #pragma unroll 1
;     for (int c = 0; c < nmain; ++c) {
;         MR_ISSUE(c + PD);
;         asm volatile("s_waitcnt vmcnt(12)" ::: "memory"); __builtin_amdgcn_s_barrier(); asm volatile("" ::: "memory");
;         MR_CONSUME(c);
;     }
.LBB0_351:
	s_add_i32 s10, s1, 0x18000
	s_and_b32 s10, s10, 0x1c000
	s_add_i32 s10, s10, s0
	s_mov_b32 m0, s10
	s_nop 0
	global_load_lds_dwordx4 v[14:15], off
	s_addk_i32 s10, 0x2000
	s_mov_b32 m0, s10
	s_nop 0
	global_load_lds_dwordx4 v[12:13], off
	v_cndmask_b32_e64 v0, 0, 1, s[14:15]
	v_cmp_ne_u32_e64 s[10:11], 1, v0
	s_and_b32 s23, s1, 0x1c000
	v_add_u32_e32 v0, s23, v20
	v_add_u32_e32 v21, v0, v18
	v_add_u32_e32 v2, s23, v19
	v_add_u32_e32 v3, v2, v18
	v_add_u32_e32 v0, v0, v17
	v_add_u32_e32 v2, v2, v17
	s_andn2_b64 vcc, exec, s[14:15]
	s_waitcnt vmcnt(12)
	s_barrier
	s_cbranch_vccnz .LBB0_350
	ds_read_b128 v[32:35], v3
	ds_read_b128 v[22:25], v21 offset:8192
	ds_read_b128 v[40:43], v21 offset:10240
	ds_read_b128 v[44:47], v21 offset:12288
	ds_read_b128 v[64:67], v21 offset:14336
	ds_read_b128 v[36:39], v2
	s_waitcnt lgkmcnt(4)
	v_mfma_f32_16x16x32_bf16 v[48:51], v[22:25], v[32:35], v[48:51]
	ds_read_b128 v[22:25], v0 offset:8192
	s_waitcnt lgkmcnt(4)
	v_mfma_f32_16x16x32_bf16 v[28:31], v[40:43], v[32:35], v[28:31]
	ds_read_b128 v[40:43], v0 offset:10240
	s_waitcnt lgkmcnt(4)
	v_mfma_f32_16x16x32_bf16 v[4:7], v[44:47], v[32:35], v[4:7]
	ds_read_b128 v[44:47], v0 offset:12288
	s_waitcnt lgkmcnt(4)
	v_mfma_f32_16x16x32_bf16 v[8:11], v[64:67], v[32:35], v[8:11]
	ds_read_b128 v[64:67], v0 offset:14336
	s_waitcnt lgkmcnt(3)
	v_mfma_f32_16x16x32_bf16 v[48:51], v[22:25], v[36:39], v[48:51]
	s_waitcnt lgkmcnt(2)
	v_mfma_f32_16x16x32_bf16 v[28:31], v[40:43], v[36:39], v[28:31]
	s_waitcnt lgkmcnt(1)
	v_mfma_f32_16x16x32_bf16 v[4:7], v[44:47], v[36:39], v[4:7]
	s_waitcnt lgkmcnt(0)
	v_mfma_f32_16x16x32_bf16 v[8:11], v[64:67], v[36:39], v[8:11]
	s_branch .LBB0_350

; #define MR_ISSUE(c) do { const unsigned sb_ = ldw + (unsigned)(((c) & (NS - 1)) * SLOT); glds16_m(src[0] + (size_t)(c) * 128, sb_); glds16_m(src[1] + (size_t)(c) * 128, sb_ + 8192u); } while (0)
; template <class Epi>
; __device__ __forceinline__ void mini_ring(PG8_LAS unsigned char* lds, const bf16_t* A, const bf16_t* Bt, int K, const Epi& E, int mu, int wave_u) {
;     ...
; #pragma unroll
;     for (int c = 0; c < PD; ++c) MR_ISSUE(c);
;     f32x4 acc[2][2];
; #pragma unroll
;     for (int b = 0; b < 2; ++b)
; #pragma unroll
;         for (int n = 0; n < 2; ++n) acc[b][n] = (f32x4){0.f, 0.f, 0.f, 0.f};
;     const int x0 = ((fq) ^ (fr & 7)) * 16, x1 = ((4 + fq) ^ (fr & 7)) * 16;
;     const int aoff = (16 * (w & 3) + fr) * 128;
;     ...
; #pragma unroll 1
;     for (int c = 0; c < nmain; ++c) {
;         MR_ISSUE(c + PD);
;         asm volatile("s_waitcnt vmcnt(12)" ::: "memory"); __builtin_amdgcn_s_barrier(); asm volatile("" ::: "memory");
;         MR_CONSUME(c);
;     }
.LBB0_1215:
	s_add_i32 s2, s1, 0x18000
	s_and_b32 s2, s2, 0x1c000
	s_add_i32 s2, s2, s0
	s_mov_b32 m0, s2
	s_nop 0
	global_load_lds_dwordx4 v[16:17], off
	s_addk_i32 s2, 0x2000
	s_mov_b32 m0, s2
	s_nop 0
	global_load_lds_dwordx4 v[14:15], off
	v_cndmask_b32_e64 v0, 0, 1, s[16:17]
	v_cmp_ne_u32_e64 s[10:11], 1, v0
	s_and_b32 s2, s1, 0x1c000
	v_add_u32_e32 v0, s2, v22
	v_add_u32_e32 v23, v0, v20
	v_add_u32_e32 v40, s2, v21
	v_add_u32_e32 v28, v40, v20
	v_add_u32_e32 v0, v0, v19
	v_add_u32_e32 v40, v40, v19
	s_andn2_b64 vcc, exec, s[16:17]
	s_waitcnt vmcnt(12)
	s_barrier
	s_cbranch_vccnz .LBB0_1214
	s_waitcnt lgkmcnt(0)
	ds_read_b128 v[28:31], v28
	ds_read_b128 v[24:27], v23 offset:8192
	ds_read_b128 v[36:39], v23 offset:10240
	ds_read_b128 v[52:55], v23 offset:12288
	ds_read_b128 v[60:63], v23 offset:14336
	ds_read_b128 v[32:35], v40
	ds_read_b128 v[64:67], v0 offset:8192
	s_waitcnt lgkmcnt(5)
	v_mfma_f32_16x16x32_bf16 v[46:49], v[24:27], v[28:31], v[46:49]
	ds_read_b128 v[24:27], v0 offset:10240
	s_waitcnt lgkmcnt(5)
	v_mfma_f32_16x16x32_bf16 v[10:13], v[36:39], v[28:31], v[10:13]
	ds_read_b128 v[36:39], v0 offset:12288
	s_waitcnt lgkmcnt(5)
	v_mfma_f32_16x16x32_bf16 v[6:9], v[52:55], v[28:31], v[6:9]
	ds_read_b128 v[52:55], v0 offset:14336
	s_waitcnt lgkmcnt(5)
	v_mfma_f32_16x16x32_bf16 v[2:5], v[60:63], v[28:31], v[2:5]
	s_waitcnt lgkmcnt(3)
	v_mfma_f32_16x16x32_bf16 v[46:49], v[64:67], v[32:35], v[46:49]
	s_waitcnt lgkmcnt(2)
	v_mfma_f32_16x16x32_bf16 v[10:13], v[24:27], v[32:35], v[10:13]
	s_waitcnt lgkmcnt(1)
	v_mfma_f32_16x16x32_bf16 v[6:9], v[36:39], v[32:35], v[6:9]
	s_waitcnt lgkmcnt(0)
	v_mfma_f32_16x16x32_bf16 v[2:5], v[52:55], v[32:35], v[2:5]
	s_branch .LBB0_1214

; #define MR_ISSUE(c) do { const unsigned sb_ = ldw + (unsigned)(((c) & (NS - 1)) * SLOT); glds16_m(src[0] + (size_t)(c) * 128, sb_); glds16_m(src[1] + (size_t)(c) * 128, sb_ + 8192u); } while (0)
; template <class Epi>
; __device__ __forceinline__ void mini_ring(PG8_LAS unsigned char* lds, const bf16_t* A, const bf16_t* Bt, int K, const Epi& E, int mu, int wave_u) {
;     ...
; #pragma unroll
;     for (int c = 0; c < PD; ++c) MR_ISSUE(c);
;     f32x4 acc[2][2];
; #pragma unroll
;     for (int b = 0; b < 2; ++b)
; #pragma unroll
;         for (int n = 0; n < 2; ++n) acc[b][n] = (f32x4){0.f, 0.f, 0.f, 0.f};
;     const int x0 = ((fq) ^ (fr & 7)) * 16, x1 = ((4 + fq) ^ (fr & 7)) * 16;
;     const int aoff = (16 * (w & 3) + fr) * 128;
;     ...
; #pragma unroll 1
;     for (int c = 0; c < nmain; ++c) {
;         MR_ISSUE(c + PD);
;         asm volatile("s_waitcnt vmcnt(12)" ::: "memory"); __builtin_amdgcn_s_barrier(); asm volatile("" ::: "memory");
;         MR_CONSUME(c);
;     }
.LBB0_1468:
	s_add_i32 s10, s1, 0x18000
	s_and_b32 s10, s10, 0x1c000
	s_add_i32 s10, s10, s0
	s_mov_b32 m0, s10
	s_nop 0
	global_load_lds_dwordx4 v[6:7], off
	s_addk_i32 s10, 0x2000
	s_mov_b32 m0, s10
	s_nop 0
	global_load_lds_dwordx4 v[4:5], off
	v_cndmask_b32_e64 v0, 0, 1, s[12:13]
	v_cmp_ne_u32_e64 s[10:11], 1, v0
	s_and_b32 s17, s1, 0x1c000
	v_add_u32_e32 v0, s17, v12
	v_add_u32_e32 v2, v0, v9
	v_add_u32_e32 v3, s17, v11
	v_add_u32_e32 v13, v3, v9
	v_add_u32_e32 v0, v0, v10
	v_add_u32_e32 v3, v3, v10
	s_andn2_b64 vcc, exec, s[12:13]
	s_waitcnt vmcnt(12)
	s_barrier
	s_cbranch_vccnz .LBB0_1467
	ds_read_b128 v[44:47], v13
	ds_read_b128 v[48:51], v2 offset:8192
	ds_read_b128 v[52:55], v2 offset:10240
	ds_read_b128 v[56:59], v2 offset:12288
	ds_read_b128 v[60:63], v2 offset:14336
	ds_read_b128 v[64:67], v3
	ds_read_b128 v[68:71], v0 offset:8192
	ds_read_b128 v[72:75], v0 offset:10240
	ds_read_b128 v[76:79], v0 offset:12288
	ds_read_b128 v[14:17], v0 offset:14336
	s_waitcnt lgkmcnt(8)
	v_mfma_f32_16x16x32_bf16 v[30:33], v[48:51], v[44:47], v[30:33]
	s_waitcnt lgkmcnt(7)
	v_mfma_f32_16x16x32_bf16 v[34:37], v[52:55], v[44:47], v[34:37]
	s_waitcnt lgkmcnt(6)
	v_mfma_f32_16x16x32_bf16 v[18:21], v[56:59], v[44:47], v[18:21]
	s_waitcnt lgkmcnt(5)
	v_mfma_f32_16x16x32_bf16 v[22:25], v[60:63], v[44:47], v[22:25]
	s_waitcnt lgkmcnt(3)
	v_mfma_f32_16x16x32_bf16 v[30:33], v[68:71], v[64:67], v[30:33]
	s_waitcnt lgkmcnt(2)
	v_mfma_f32_16x16x32_bf16 v[34:37], v[72:75], v[64:67], v[34:37]
	s_waitcnt lgkmcnt(1)
	v_mfma_f32_16x16x32_bf16 v[18:21], v[76:79], v[64:67], v[18:21]
	s_waitcnt lgkmcnt(0)
	v_mfma_f32_16x16x32_bf16 v[22:25], v[14:17], v[64:67], v[22:25]
	s_branch .LBB0_1467
